# fused LN epilogues: the 16 bf16 residual loads per wave issued together up front and consumed with counted waits
# speedup vs baseline: 1.0133x; 1.0035x over previous
.LBB0_2149:
	s_lshl_b32 s4, s62, 5
	s_lshl_b32 s5, s24, 8
	v_lshrrev_b32_e32 v16, 1, v150
	s_or_b32 s4, s5, s4
	s_lshl_b32 s36, s22, 8
	v_and_or_b32 v162, v16, 24, s4
	s_add_i32 s4, s36, s87
	v_or_b32_e32 v146, s4, v151
	v_ashrrev_i32_e32 v147, 31, v146
	v_ashrrev_i32_e32 v163, 31, v162
	v_lshlrev_b64 v[130:131], 10, v[146:147]
	v_readlane_b32 s6, v255, 8
	v_lshl_add_u64 v[148:149], v[130:131], 0, v[162:163]
	s_and_b64 vcc, exec, s[10:11]
	s_cbranch_vccz pfr_f32_1
	v_lshlrev_b32_e32 v182, 1, v148
	global_load_dwordx4 v[184:187], v182, s[16:17]
	global_load_dwordx4 v[188:191], v182, s[16:17] offset:256
	v_add_u32_e32 v183, 0x8000, v182
	global_load_dwordx4 v[192:195], v183, s[16:17]
	global_load_dwordx4 v[196:199], v183, s[16:17] offset:256
	v_add_u32_e32 v183, 0x10000, v182
	global_load_dwordx4 v[200:203], v183, s[16:17]
	global_load_dwordx4 v[204:207], v183, s[16:17] offset:256
	v_add_u32_e32 v183, 0x18000, v182
	global_load_dwordx4 v[208:211], v183, s[16:17]
	global_load_dwordx4 v[212:215], v183, s[16:17] offset:256
	v_add_u32_e32 v183, 0x40000, v182
	global_load_dwordx4 v[216:219], v183, s[16:17]
	global_load_dwordx4 v[220:223], v183, s[16:17] offset:256
	v_add_u32_e32 v183, 0x48000, v182
	global_load_dwordx4 v[224:227], v183, s[16:17]
	global_load_dwordx4 v[228:231], v183, s[16:17] offset:256
	v_add_u32_e32 v183, 0x50000, v182
	global_load_dwordx4 v[232:235], v183, s[16:17]
	global_load_dwordx4 v[152:155], v183, s[16:17] offset:256
	v_add_u32_e32 v183, 0x58000, v182
	global_load_dwordx4 v[156:159], v183, s[16:17]
	global_load_dwordx4 v[166:169], v183, s[16:17] offset:256
	s_branch pfr_done_1
pfr_f32_1:
	v_lshlrev_b32_e32 v182, 2, v148
	global_load_dwordx4 v[184:187], v182, s[8:9]
	global_load_dwordx4 v[184:187], v182, s[8:9] offset:512
	v_add_u32_e32 v183, 0x10000, v182
	global_load_dwordx4 v[184:187], v183, s[8:9]
	global_load_dwordx4 v[184:187], v183, s[8:9] offset:512
	v_add_u32_e32 v183, 0x20000, v182
	global_load_dwordx4 v[184:187], v183, s[8:9]
	global_load_dwordx4 v[184:187], v183, s[8:9] offset:512
	v_add_u32_e32 v183, 0x30000, v182
	global_load_dwordx4 v[184:187], v183, s[8:9]
	global_load_dwordx4 v[184:187], v183, s[8:9] offset:512
	v_add_u32_e32 v183, 0x80000, v182
	global_load_dwordx4 v[184:187], v183, s[8:9]
	global_load_dwordx4 v[184:187], v183, s[8:9] offset:512
	v_add_u32_e32 v183, 0x90000, v182
	global_load_dwordx4 v[184:187], v183, s[8:9]
	global_load_dwordx4 v[184:187], v183, s[8:9] offset:512
	v_add_u32_e32 v183, 0xa0000, v182
	global_load_dwordx4 v[184:187], v183, s[8:9]
	global_load_dwordx4 v[184:187], v183, s[8:9] offset:512
	v_add_u32_e32 v183, 0xb0000, v182
	global_load_dwordx4 v[184:187], v183, s[8:9]
	global_load_dwordx4 v[184:187], v183, s[8:9] offset:512
pfr_done_1:
	s_mov_b64 s[4:5], -1
	s_and_b64 vcc, exec, s[10:11]
	s_mov_b32 s80, s6
	s_movk_i32 s90, 0x1dbf
	s_movk_i32 s91, 0x210
	s_movk_i32 s88, 0x1600
	s_mov_b32 s89, 0x16000
	s_mov_b32 s94, 0x3fb504f3
	s_barrier
	v_readlane_b32 s7, v255, 9
	s_cbranch_vccz .LBB0_2151
	v_lshl_add_u64 v[130:131], v[148:149], 1, s[16:17]
	s_waitcnt vmcnt(15)
	v_mov_b32_e32 v134, v184
	v_mov_b32_e32 v135, v185
	v_mov_b32_e32 v136, v186
	v_mov_b32_e32 v137, v187
	s_mov_b64 s[4:5], 0
	v_lshlrev_b32_e32 v130, 16, v134
	v_and_b32_e32 v131, 0xffff0000, v134
	v_lshlrev_b32_e32 v132, 16, v135
	v_and_b32_e32 v133, 0xffff0000, v135
	v_lshlrev_b32_e32 v134, 16, v136
	v_and_b32_e32 v135, 0xffff0000, v136
	v_lshlrev_b32_e32 v136, 16, v137
	v_and_b32_e32 v137, 0xffff0000, v137

.LBB0_2153:
	v_cndmask_b32_e64 v16, 0, 1, s[10:11]
	v_cmp_ne_u32_e64 s[4:5], 1, v16
	s_andn2_b64 vcc, exec, s[10:11]
	s_mov_b64 s[6:7], -1
	s_cbranch_vccnz .LBB0_2155
	v_lshl_add_u64 v[138:139], v[148:149], 1, s[16:17]
	s_waitcnt vmcnt(14)
	v_mov_b32_e32 v142, v188
	v_mov_b32_e32 v143, v189
	v_mov_b32_e32 v144, v190
	v_mov_b32_e32 v145, v191
	s_mov_b64 s[6:7], 0
	v_lshlrev_b32_e32 v138, 16, v142
	v_and_b32_e32 v139, 0xffff0000, v142
	v_lshlrev_b32_e32 v140, 16, v143
	v_and_b32_e32 v141, 0xffff0000, v143
	v_lshlrev_b32_e32 v142, 16, v144
	v_and_b32_e32 v143, 0xffff0000, v144
	v_lshlrev_b32_e32 v144, 16, v145
	v_and_b32_e32 v145, 0xffff0000, v145

.LBB0_2157:
	s_waitcnt vmcnt(0)
	v_pk_fma_f32 v[42:43], v[130:131], s[94:95], v[42:43] op_sel_hi:[1,0,1]
	v_or_b32_e32 v130, 16, v146
	v_ashrrev_i32_e32 v131, 31, v130
	v_lshlrev_b64 v[130:131], 10, v[130:131]
	v_pk_fma_f32 v[44:45], v[132:133], s[94:95], v[44:45] op_sel_hi:[1,0,1]
	v_pk_fma_f32 v[48:49], v[136:137], s[94:95], v[48:49] op_sel_hi:[1,0,1]
	v_pk_fma_f32 v[46:47], v[134:135], s[94:95], v[46:47] op_sel_hi:[1,0,1]
	v_pk_fma_f32 v[40:41], v[140:141], s[94:95], v[40:41] op_sel_hi:[1,0,1]
	v_pk_fma_f32 v[38:39], v[138:139], s[94:95], v[38:39] op_sel_hi:[1,0,1]
	v_pk_fma_f32 v[28:29], v[144:145], s[94:95], v[28:29] op_sel_hi:[1,0,1]
	v_pk_fma_f32 v[26:27], v[142:143], s[94:95], v[26:27] op_sel_hi:[1,0,1]
	v_lshl_add_u64 v[148:149], v[130:131], 0, v[162:163]
	s_and_b64 vcc, exec, s[4:5]
	s_mov_b64 s[6:7], -1
	s_cbranch_vccnz .LBB0_2159
	v_lshl_add_u64 v[130:131], v[148:149], 1, s[16:17]
	s_waitcnt vmcnt(13)
	v_mov_b32_e32 v134, v192
	v_mov_b32_e32 v135, v193
	v_mov_b32_e32 v136, v194
	v_mov_b32_e32 v137, v195
	v_lshlrev_b32_e32 v130, 16, v134
	v_and_b32_e32 v131, 0xffff0000, v134
	v_lshlrev_b32_e32 v132, 16, v135
	v_and_b32_e32 v133, 0xffff0000, v135
	v_lshlrev_b32_e32 v134, 16, v136
	v_and_b32_e32 v135, 0xffff0000, v136
	v_lshlrev_b32_e32 v136, 16, v137
	v_and_b32_e32 v137, 0xffff0000, v137
	s_cbranch_execnz .LBB0_2161
	s_branch .LBB0_2160

.LBB0_2161:
	s_and_b64 vcc, exec, s[4:5]
	s_mov_b64 s[6:7], -1
	s_cbranch_vccnz .LBB0_2163
	v_lshl_add_u64 v[138:139], v[148:149], 1, s[16:17]
	s_waitcnt vmcnt(12)
	v_mov_b32_e32 v142, v196
	v_mov_b32_e32 v143, v197
	v_mov_b32_e32 v144, v198
	v_mov_b32_e32 v145, v199
	v_lshlrev_b32_e32 v138, 16, v142
	v_and_b32_e32 v139, 0xffff0000, v142
	v_lshlrev_b32_e32 v140, 16, v143
	v_and_b32_e32 v141, 0xffff0000, v143
	v_lshlrev_b32_e32 v142, 16, v144
	v_and_b32_e32 v143, 0xffff0000, v144
	v_lshlrev_b32_e32 v144, 16, v145
	v_and_b32_e32 v145, 0xffff0000, v145
	s_cbranch_execz .LBB0_2164
	s_branch .LBB0_2165

.LBB0_2165:
	s_waitcnt vmcnt(0)
	v_pk_fma_f32 v[36:37], v[132:133], s[94:95], v[36:37] op_sel_hi:[1,0,1]
	v_pk_fma_f32 v[34:35], v[130:131], s[94:95], v[34:35] op_sel_hi:[1,0,1]
	v_pk_fma_f32 v[32:33], v[136:137], s[94:95], v[32:33] op_sel_hi:[1,0,1]
	v_pk_fma_f32 v[30:31], v[134:135], s[94:95], v[30:31] op_sel_hi:[1,0,1]
	v_pk_fma_f32 v[24:25], v[140:141], s[94:95], v[24:25] op_sel_hi:[1,0,1]
	v_pk_fma_f32 v[22:23], v[138:139], s[94:95], v[22:23] op_sel_hi:[1,0,1]
	v_pk_fma_f32 v[20:21], v[144:145], s[94:95], v[20:21] op_sel_hi:[1,0,1]
	v_pk_fma_f32 v[18:19], v[142:143], s[94:95], v[18:19] op_sel_hi:[1,0,1]
	v_or_b32_e32 v130, 32, v146
	v_ashrrev_i32_e32 v131, 31, v130
	v_lshlrev_b64 v[130:131], 10, v[130:131]
	v_lshl_add_u64 v[148:149], v[130:131], 0, v[162:163]
	s_and_b64 vcc, exec, s[4:5]
	s_mov_b64 s[6:7], -1
	s_cbranch_vccnz .LBB0_2167
	v_lshl_add_u64 v[130:131], v[148:149], 1, s[16:17]
	s_waitcnt vmcnt(11)
	v_mov_b32_e32 v134, v200
	v_mov_b32_e32 v135, v201
	v_mov_b32_e32 v136, v202
	v_mov_b32_e32 v137, v203
	v_lshlrev_b32_e32 v130, 16, v134
	v_and_b32_e32 v131, 0xffff0000, v134
	v_lshlrev_b32_e32 v132, 16, v135
	v_and_b32_e32 v133, 0xffff0000, v135
	v_lshlrev_b32_e32 v134, 16, v136
	v_and_b32_e32 v135, 0xffff0000, v136
	v_lshlrev_b32_e32 v136, 16, v137
	v_and_b32_e32 v137, 0xffff0000, v137
	s_cbranch_execnz .LBB0_2169
	s_branch .LBB0_2168

.LBB0_2169:
	s_and_b64 vcc, exec, s[4:5]
	s_mov_b64 s[6:7], -1
	s_cbranch_vccnz .LBB0_2171
	v_lshl_add_u64 v[138:139], v[148:149], 1, s[16:17]
	s_waitcnt vmcnt(10)
	v_mov_b32_e32 v142, v204
	v_mov_b32_e32 v143, v205
	v_mov_b32_e32 v144, v206
	v_mov_b32_e32 v145, v207
	v_lshlrev_b32_e32 v138, 16, v142
	v_and_b32_e32 v139, 0xffff0000, v142
	v_lshlrev_b32_e32 v140, 16, v143
	v_and_b32_e32 v141, 0xffff0000, v143
	v_lshlrev_b32_e32 v142, 16, v144
	v_and_b32_e32 v143, 0xffff0000, v144
	v_lshlrev_b32_e32 v144, 16, v145
	v_and_b32_e32 v145, 0xffff0000, v145
	s_cbranch_execz .LBB0_2172
	s_branch .LBB0_2173

.LBB0_2173:
	s_waitcnt vmcnt(0)
	v_pk_fma_f32 v[70:71], v[130:131], s[94:95], v[70:71] op_sel_hi:[1,0,1]
	v_or_b32_e32 v130, 48, v146
	v_ashrrev_i32_e32 v131, 31, v130
	v_lshlrev_b64 v[130:131], 10, v[130:131]
	v_pk_fma_f32 v[72:73], v[132:133], s[94:95], v[72:73] op_sel_hi:[1,0,1]
	v_pk_fma_f32 v[68:69], v[136:137], s[94:95], v[68:69] op_sel_hi:[1,0,1]
	v_pk_fma_f32 v[66:67], v[134:135], s[94:95], v[66:67] op_sel_hi:[1,0,1]
	v_pk_fma_f32 v[64:65], v[140:141], s[94:95], v[64:65] op_sel_hi:[1,0,1]
	v_pk_fma_f32 v[62:63], v[138:139], s[94:95], v[62:63] op_sel_hi:[1,0,1]
	v_pk_fma_f32 v[60:61], v[144:145], s[94:95], v[60:61] op_sel_hi:[1,0,1]
	v_pk_fma_f32 v[58:59], v[142:143], s[94:95], v[58:59] op_sel_hi:[1,0,1]
	v_lshl_add_u64 v[148:149], v[130:131], 0, v[162:163]
	s_and_b64 vcc, exec, s[4:5]
	s_mov_b64 s[6:7], -1
	s_cbranch_vccnz .LBB0_2175
	v_lshl_add_u64 v[130:131], v[148:149], 1, s[16:17]
	s_waitcnt vmcnt(9)
	v_mov_b32_e32 v134, v208
	v_mov_b32_e32 v135, v209
	v_mov_b32_e32 v136, v210
	v_mov_b32_e32 v137, v211
	v_lshlrev_b32_e32 v130, 16, v134
	v_and_b32_e32 v131, 0xffff0000, v134
	v_lshlrev_b32_e32 v132, 16, v135
	v_and_b32_e32 v133, 0xffff0000, v135
	v_lshlrev_b32_e32 v134, 16, v136
	v_and_b32_e32 v135, 0xffff0000, v136
	v_lshlrev_b32_e32 v136, 16, v137
	v_and_b32_e32 v137, 0xffff0000, v137
	s_cbranch_execnz .LBB0_2177
	s_branch .LBB0_2176

.LBB0_2177:
	s_and_b64 vcc, exec, s[4:5]
	s_mov_b64 s[6:7], -1
	s_cbranch_vccnz .LBB0_2179
	v_lshl_add_u64 v[138:139], v[148:149], 1, s[16:17]
	s_waitcnt vmcnt(8)
	v_mov_b32_e32 v142, v212
	v_mov_b32_e32 v143, v213
	v_mov_b32_e32 v144, v214
	v_mov_b32_e32 v145, v215
	v_lshlrev_b32_e32 v138, 16, v142
	v_and_b32_e32 v139, 0xffff0000, v142
	v_lshlrev_b32_e32 v140, 16, v143
	v_and_b32_e32 v141, 0xffff0000, v143
	v_lshlrev_b32_e32 v142, 16, v144
	v_and_b32_e32 v143, 0xffff0000, v144
	v_lshlrev_b32_e32 v144, 16, v145
	v_and_b32_e32 v145, 0xffff0000, v145
	s_cbranch_execz .LBB0_2180
	s_branch .LBB0_2181

.LBB0_2181:
	s_waitcnt vmcnt(0)
	v_pk_fma_f32 v[96:97], v[132:133], s[94:95], v[96:97] op_sel_hi:[1,0,1]
	v_pk_fma_f32 v[94:95], v[130:131], s[94:95], v[94:95] op_sel_hi:[1,0,1]
	v_pk_fma_f32 v[92:93], v[136:137], s[94:95], v[92:93] op_sel_hi:[1,0,1]
	v_pk_fma_f32 v[90:91], v[134:135], s[94:95], v[90:91] op_sel_hi:[1,0,1]
	v_pk_fma_f32 v[88:89], v[140:141], s[94:95], v[88:89] op_sel_hi:[1,0,1]
	v_pk_fma_f32 v[86:87], v[138:139], s[94:95], v[86:87] op_sel_hi:[1,0,1]
	v_pk_fma_f32 v[84:85], v[144:145], s[94:95], v[84:85] op_sel_hi:[1,0,1]
	v_pk_fma_f32 v[82:83], v[142:143], s[94:95], v[82:83] op_sel_hi:[1,0,1]
	v_add_u32_e32 v130, 0x80, v146
	v_ashrrev_i32_e32 v131, 31, v130
	v_lshlrev_b64 v[130:131], 10, v[130:131]
	v_lshl_add_u64 v[148:149], v[130:131], 0, v[162:163]
	s_and_b64 vcc, exec, s[4:5]
	s_mov_b64 s[6:7], -1
	s_cbranch_vccnz .LBB0_2183
	v_lshl_add_u64 v[130:131], v[148:149], 1, s[16:17]
	s_waitcnt vmcnt(7)
	v_mov_b32_e32 v134, v216
	v_mov_b32_e32 v135, v217
	v_mov_b32_e32 v136, v218
	v_mov_b32_e32 v137, v219
	v_lshlrev_b32_e32 v130, 16, v134
	v_and_b32_e32 v131, 0xffff0000, v134
	v_lshlrev_b32_e32 v132, 16, v135
	v_and_b32_e32 v133, 0xffff0000, v135
	v_lshlrev_b32_e32 v134, 16, v136
	v_and_b32_e32 v135, 0xffff0000, v136
	v_lshlrev_b32_e32 v136, 16, v137
	v_and_b32_e32 v137, 0xffff0000, v137
	s_cbranch_execnz .LBB0_2185
	s_branch .LBB0_2184

.LBB0_2185:
	s_and_b64 vcc, exec, s[4:5]
	s_mov_b64 s[6:7], -1
	s_cbranch_vccnz .LBB0_2187
	v_lshl_add_u64 v[138:139], v[148:149], 1, s[16:17]
	s_waitcnt vmcnt(6)
	v_mov_b32_e32 v142, v220
	v_mov_b32_e32 v143, v221
	v_mov_b32_e32 v144, v222
	v_mov_b32_e32 v145, v223
	v_lshlrev_b32_e32 v138, 16, v142
	v_and_b32_e32 v139, 0xffff0000, v142
	v_lshlrev_b32_e32 v140, 16, v143
	v_and_b32_e32 v141, 0xffff0000, v143
	v_lshlrev_b32_e32 v142, 16, v144
	v_and_b32_e32 v143, 0xffff0000, v144
	v_lshlrev_b32_e32 v144, 16, v145
	v_and_b32_e32 v145, 0xffff0000, v145
	s_cbranch_execz .LBB0_2188
	s_branch .LBB0_2189

.LBB0_2189:
	s_waitcnt vmcnt(0)
	v_pk_fma_f32 v[118:119], v[130:131], s[94:95], v[118:119] op_sel_hi:[1,0,1]
	v_add_u32_e32 v130, 0x90, v146
	v_ashrrev_i32_e32 v131, 31, v130
	v_lshlrev_b64 v[130:131], 10, v[130:131]
	v_pk_fma_f32 v[120:121], v[132:133], s[94:95], v[120:121] op_sel_hi:[1,0,1]
	v_pk_fma_f32 v[116:117], v[136:137], s[94:95], v[116:117] op_sel_hi:[1,0,1]
	v_pk_fma_f32 v[114:115], v[134:135], s[94:95], v[114:115] op_sel_hi:[1,0,1]
	v_pk_fma_f32 v[112:113], v[140:141], s[94:95], v[112:113] op_sel_hi:[1,0,1]
	v_pk_fma_f32 v[110:111], v[138:139], s[94:95], v[110:111] op_sel_hi:[1,0,1]
	v_pk_fma_f32 v[104:105], v[144:145], s[94:95], v[104:105] op_sel_hi:[1,0,1]
	v_pk_fma_f32 v[102:103], v[142:143], s[94:95], v[102:103] op_sel_hi:[1,0,1]
	v_lshl_add_u64 v[148:149], v[130:131], 0, v[162:163]
	s_and_b64 vcc, exec, s[4:5]
	s_mov_b64 s[6:7], -1
	s_cbranch_vccnz .LBB0_2191
	v_lshl_add_u64 v[130:131], v[148:149], 1, s[16:17]
	s_waitcnt vmcnt(5)
	v_mov_b32_e32 v134, v224
	v_mov_b32_e32 v135, v225
	v_mov_b32_e32 v136, v226
	v_mov_b32_e32 v137, v227
	v_lshlrev_b32_e32 v130, 16, v134
	v_and_b32_e32 v131, 0xffff0000, v134
	v_lshlrev_b32_e32 v132, 16, v135
	v_and_b32_e32 v133, 0xffff0000, v135
	v_lshlrev_b32_e32 v134, 16, v136
	v_and_b32_e32 v135, 0xffff0000, v136
	v_lshlrev_b32_e32 v136, 16, v137
	v_and_b32_e32 v137, 0xffff0000, v137
	s_cbranch_execnz .LBB0_2193
	s_branch .LBB0_2192

.LBB0_2193:
	s_and_b64 vcc, exec, s[4:5]
	s_mov_b64 s[6:7], -1
	s_cbranch_vccnz .LBB0_2195
	v_lshl_add_u64 v[138:139], v[148:149], 1, s[16:17]
	s_waitcnt vmcnt(4)
	v_mov_b32_e32 v142, v228
	v_mov_b32_e32 v143, v229
	v_mov_b32_e32 v144, v230
	v_mov_b32_e32 v145, v231
	v_lshlrev_b32_e32 v138, 16, v142
	v_and_b32_e32 v139, 0xffff0000, v142
	v_lshlrev_b32_e32 v140, 16, v143
	v_and_b32_e32 v141, 0xffff0000, v143
	v_lshlrev_b32_e32 v142, 16, v144
	v_and_b32_e32 v143, 0xffff0000, v144
	v_lshlrev_b32_e32 v144, 16, v145
	v_and_b32_e32 v145, 0xffff0000, v145
	s_cbranch_execz .LBB0_2196
	s_branch .LBB0_2197

.LBB0_2197:
	s_waitcnt vmcnt(0)
	v_pk_fma_f32 v[128:129], v[132:133], s[94:95], v[128:129] op_sel_hi:[1,0,1]
	v_pk_fma_f32 v[126:127], v[130:131], s[94:95], v[126:127] op_sel_hi:[1,0,1]
	v_pk_fma_f32 v[124:125], v[136:137], s[94:95], v[124:125] op_sel_hi:[1,0,1]
	v_pk_fma_f32 v[122:123], v[134:135], s[94:95], v[122:123] op_sel_hi:[1,0,1]
	v_pk_fma_f32 v[108:109], v[140:141], s[94:95], v[108:109] op_sel_hi:[1,0,1]
	v_pk_fma_f32 v[106:107], v[138:139], s[94:95], v[106:107] op_sel_hi:[1,0,1]
	v_pk_fma_f32 v[100:101], v[144:145], s[94:95], v[100:101] op_sel_hi:[1,0,1]
	v_pk_fma_f32 v[98:99], v[142:143], s[94:95], v[98:99] op_sel_hi:[1,0,1]
	v_add_u32_e32 v130, 0xa0, v146
	v_ashrrev_i32_e32 v131, 31, v130
	v_lshlrev_b64 v[130:131], 10, v[130:131]
	v_lshl_add_u64 v[148:149], v[130:131], 0, v[162:163]
	s_and_b64 vcc, exec, s[4:5]
	s_mov_b64 s[6:7], -1
	s_cbranch_vccnz .LBB0_2199
	v_lshl_add_u64 v[130:131], v[148:149], 1, s[16:17]
	s_waitcnt vmcnt(3)
	v_mov_b32_e32 v134, v232
	v_mov_b32_e32 v135, v233
	v_mov_b32_e32 v136, v234
	v_mov_b32_e32 v137, v235
	v_lshlrev_b32_e32 v130, 16, v134
	v_and_b32_e32 v131, 0xffff0000, v134
	v_lshlrev_b32_e32 v132, 16, v135
	v_and_b32_e32 v133, 0xffff0000, v135
	v_lshlrev_b32_e32 v134, 16, v136
	v_and_b32_e32 v135, 0xffff0000, v136
	v_lshlrev_b32_e32 v136, 16, v137
	v_and_b32_e32 v137, 0xffff0000, v137
	s_cbranch_execnz .LBB0_2201
	s_branch .LBB0_2200

.LBB0_2201:
	s_and_b64 vcc, exec, s[4:5]
	s_mov_b64 s[6:7], -1
	s_cbranch_vccnz .LBB0_2203
	v_lshl_add_u64 v[138:139], v[148:149], 1, s[16:17]
	s_waitcnt vmcnt(2)
	v_mov_b32_e32 v142, v152
	v_mov_b32_e32 v143, v153
	v_mov_b32_e32 v144, v154
	v_mov_b32_e32 v145, v155
	v_lshlrev_b32_e32 v138, 16, v142
	v_and_b32_e32 v139, 0xffff0000, v142
	v_lshlrev_b32_e32 v140, 16, v143
	v_and_b32_e32 v141, 0xffff0000, v143
	v_lshlrev_b32_e32 v142, 16, v144
	v_and_b32_e32 v143, 0xffff0000, v144
	v_lshlrev_b32_e32 v144, 16, v145
	v_and_b32_e32 v145, 0xffff0000, v145
	s_cbranch_execz .LBB0_2204
	s_branch .LBB0_2205

.LBB0_2205:
	s_waitcnt vmcnt(0)
	v_pk_fma_f32 v[78:79], v[130:131], s[94:95], v[78:79] op_sel_hi:[1,0,1]
	v_add_u32_e32 v130, 0xb0, v146
	v_ashrrev_i32_e32 v131, 31, v130
	v_lshlrev_b64 v[130:131], 10, v[130:131]
	v_pk_fma_f32 v[80:81], v[132:133], s[94:95], v[80:81] op_sel_hi:[1,0,1]
	v_pk_fma_f32 v[76:77], v[136:137], s[94:95], v[76:77] op_sel_hi:[1,0,1]
	v_pk_fma_f32 v[74:75], v[134:135], s[94:95], v[74:75] op_sel_hi:[1,0,1]
	v_pk_fma_f32 v[56:57], v[140:141], s[94:95], v[56:57] op_sel_hi:[1,0,1]
	v_pk_fma_f32 v[54:55], v[138:139], s[94:95], v[54:55] op_sel_hi:[1,0,1]
	v_pk_fma_f32 v[52:53], v[144:145], s[94:95], v[52:53] op_sel_hi:[1,0,1]
	v_pk_fma_f32 v[50:51], v[142:143], s[94:95], v[50:51] op_sel_hi:[1,0,1]
	v_lshl_add_u64 v[146:147], v[130:131], 0, v[162:163]
	s_and_b64 vcc, exec, s[4:5]
	s_mov_b64 s[6:7], -1
	s_cbranch_vccnz .LBB0_2207
	v_lshl_add_u64 v[130:131], v[146:147], 1, s[16:17]
	s_waitcnt vmcnt(1)
	v_mov_b32_e32 v134, v156
	v_mov_b32_e32 v135, v157
	v_mov_b32_e32 v136, v158
	v_mov_b32_e32 v137, v159
	v_lshlrev_b32_e32 v130, 16, v134
	v_and_b32_e32 v131, 0xffff0000, v134
	v_lshlrev_b32_e32 v132, 16, v135
	v_and_b32_e32 v133, 0xffff0000, v135
	v_lshlrev_b32_e32 v134, 16, v136
	v_and_b32_e32 v135, 0xffff0000, v136
	v_lshlrev_b32_e32 v136, 16, v137
	v_and_b32_e32 v137, 0xffff0000, v137
	s_cbranch_execnz .LBB0_2209
	s_branch .LBB0_2208

.LBB0_2209:
	s_and_b64 vcc, exec, s[4:5]
	s_mov_b64 s[4:5], -1
	s_cbranch_vccnz .LBB0_2211
	v_lshl_add_u64 v[138:139], v[146:147], 1, s[16:17]
	s_waitcnt vmcnt(0)
	v_mov_b32_e32 v142, v166
	v_mov_b32_e32 v143, v167
	v_mov_b32_e32 v144, v168
	v_mov_b32_e32 v145, v169
	v_lshlrev_b32_e32 v138, 16, v142
	v_and_b32_e32 v139, 0xffff0000, v142
	v_lshlrev_b32_e32 v140, 16, v143
	v_and_b32_e32 v141, 0xffff0000, v143
	v_lshlrev_b32_e32 v142, 16, v144
	v_and_b32_e32 v143, 0xffff0000, v144
	v_lshlrev_b32_e32 v144, 16, v145
	v_and_b32_e32 v145, 0xffff0000, v145
	s_cbranch_execz .LBB0_2212
	s_branch .LBB0_2213

.LBB0_2543:
	s_lshl_b32 s4, s55, 5
	s_lshl_b32 s5, s26, 8
	v_lshrrev_b32_e32 v130, 1, v144
	s_or_b32 s4, s5, s4
	s_lshl_b32 s38, s50, 8
	v_and_or_b32 v162, v130, 24, s4
	s_add_i32 s4, s38, s69
	v_or_b32_e32 v138, s4, v145
	v_ashrrev_i32_e32 v139, 31, v138
	v_ashrrev_i32_e32 v163, 31, v162
	v_lshlrev_b64 v[130:131], 11, v[138:139]
	v_lshl_add_u64 v[130:131], s[28:29], 0, v[130:131]
	v_lshlrev_b64 v[140:141], 1, v[162:163]
	v_lshl_add_u64 v[134:135], v[130:131], 0, v[140:141]
	global_load_dwordx4 v[184:187], v[134:135], off
	global_load_dwordx4 v[188:191], v[134:135], off offset:256
	s_mov_b64 s[100:101], 0x8000
	v_lshl_add_u64 v[182:183], v[134:135], 0, s[100:101]
	global_load_dwordx4 v[192:195], v[182:183], off
	global_load_dwordx4 v[196:199], v[182:183], off offset:256
	s_mov_b64 s[100:101], 0x10000
	v_lshl_add_u64 v[182:183], v[134:135], 0, s[100:101]
	global_load_dwordx4 v[200:203], v[182:183], off
	global_load_dwordx4 v[204:207], v[182:183], off offset:256
	s_mov_b64 s[100:101], 0x18000
	v_lshl_add_u64 v[182:183], v[134:135], 0, s[100:101]
	global_load_dwordx4 v[208:211], v[182:183], off
	global_load_dwordx4 v[212:215], v[182:183], off offset:256
	s_mov_b64 s[100:101], 0x40000
	v_lshl_add_u64 v[182:183], v[134:135], 0, s[100:101]
	global_load_dwordx4 v[216:219], v[182:183], off
	global_load_dwordx4 v[220:223], v[182:183], off offset:256
	s_mov_b64 s[100:101], 0x48000
	v_lshl_add_u64 v[182:183], v[134:135], 0, s[100:101]
	global_load_dwordx4 v[224:227], v[182:183], off
	global_load_dwordx4 v[228:231], v[182:183], off offset:256
	s_mov_b64 s[100:101], 0x50000
	v_lshl_add_u64 v[182:183], v[134:135], 0, s[100:101]
	global_load_dwordx4 v[232:235], v[182:183], off
	global_load_dwordx4 v[148:151], v[182:183], off offset:256
	s_mov_b64 s[100:101], 0x58000
	v_lshl_add_u64 v[182:183], v[134:135], 0, s[100:101]
	global_load_dwordx4 v[152:155], v[182:183], off
	global_load_dwordx4 v[156:159], v[182:183], off offset:256
	s_barrier
	v_and_b32_e32 v16, 63, v144
	s_lshl_b32 s4, s55, 3
	s_add_i32 s6, s97, s4
	s_waitcnt vmcnt(15)
	v_mov_b32_e32 v130, v184
	v_mov_b32_e32 v131, v185
	v_mov_b32_e32 v132, v186
	v_mov_b32_e32 v133, v187
	v_lshlrev_b32_e32 v136, 16, v130
	v_and_b32_e32 v137, 0xffff0000, v130
	v_lshlrev_b32_e32 v130, 16, v131
	v_and_b32_e32 v131, 0xffff0000, v131
	v_lshlrev_b32_e32 v142, 16, v132
	v_and_b32_e32 v143, 0xffff0000, v132
	v_lshlrev_b32_e32 v132, 16, v133
	v_and_b32_e32 v133, 0xffff0000, v133
	v_pk_fma_f32 v[32:33], v[130:131], s[94:95], v[32:33] op_sel_hi:[1,0,1]
	v_pk_fma_f32 v[24:25], v[132:133], s[94:95], v[24:25] op_sel_hi:[1,0,1]
	v_pk_fma_f32 v[30:31], v[136:137], s[94:95], v[30:31] op_sel_hi:[1,0,1]
	v_pk_fma_f32 v[22:23], v[142:143], s[94:95], v[22:23] op_sel_hi:[1,0,1]
	s_waitcnt vmcnt(14)
	v_mov_b32_e32 v130, v188
	v_mov_b32_e32 v131, v189
	v_mov_b32_e32 v132, v190
	v_mov_b32_e32 v133, v191
	v_lshlrev_b32_e32 v134, 16, v130
	v_and_b32_e32 v135, 0xffff0000, v130
	v_lshlrev_b32_e32 v130, 16, v131
	v_and_b32_e32 v131, 0xffff0000, v131
	v_pk_fma_f32 v[6:7], v[130:131], s[94:95], v[6:7] op_sel_hi:[1,0,1]
	v_or_b32_e32 v130, 16, v138
	v_ashrrev_i32_e32 v131, 31, v130
	v_lshlrev_b64 v[130:131], 11, v[130:131]
	v_lshlrev_b32_e32 v136, 16, v132
	v_and_b32_e32 v137, 0xffff0000, v132
	v_lshlrev_b32_e32 v132, 16, v133
	v_and_b32_e32 v133, 0xffff0000, v133
	v_lshl_add_u64 v[130:131], s[28:29], 0, v[130:131]
	v_pk_fma_f32 v[4:5], v[134:135], s[94:95], v[4:5] op_sel_hi:[1,0,1]
	v_pk_fma_f32 v[2:3], v[132:133], s[94:95], v[2:3] op_sel_hi:[1,0,1]
	v_pk_fma_f32 v[0:1], v[136:137], s[94:95], v[0:1] op_sel_hi:[1,0,1]
	v_lshl_add_u64 v[134:135], v[130:131], 0, v[140:141]
	s_waitcnt vmcnt(13)
	v_mov_b32_e32 v130, v192
	v_mov_b32_e32 v131, v193
	v_mov_b32_e32 v132, v194
	v_mov_b32_e32 v133, v195
	v_lshlrev_b32_e32 v136, 16, v130
	v_and_b32_e32 v137, 0xffff0000, v130
	v_lshlrev_b32_e32 v130, 16, v131
	v_and_b32_e32 v131, 0xffff0000, v131
	v_lshlrev_b32_e32 v142, 16, v132
	v_and_b32_e32 v143, 0xffff0000, v132
	v_lshlrev_b32_e32 v132, 16, v133
	v_and_b32_e32 v133, 0xffff0000, v133
	v_pk_fma_f32 v[28:29], v[130:131], s[94:95], v[28:29] op_sel_hi:[1,0,1]
	v_pk_fma_f32 v[14:15], v[132:133], s[94:95], v[14:15] op_sel_hi:[1,0,1]
	v_pk_fma_f32 v[26:27], v[136:137], s[94:95], v[26:27] op_sel_hi:[1,0,1]
	v_pk_fma_f32 v[12:13], v[142:143], s[94:95], v[12:13] op_sel_hi:[1,0,1]
	s_waitcnt vmcnt(12)
	v_mov_b32_e32 v130, v196
	v_mov_b32_e32 v131, v197
	v_mov_b32_e32 v132, v198
	v_mov_b32_e32 v133, v199
	v_lshlrev_b32_e32 v134, 16, v130
	v_and_b32_e32 v135, 0xffff0000, v130
	v_lshlrev_b32_e32 v130, 16, v131
	v_and_b32_e32 v131, 0xffff0000, v131
	v_pk_fma_f32 v[20:21], v[130:131], s[94:95], v[20:21] op_sel_hi:[1,0,1]
	v_or_b32_e32 v130, 32, v138
	v_ashrrev_i32_e32 v131, 31, v130
	v_lshlrev_b32_e32 v136, 16, v132
	v_and_b32_e32 v137, 0xffff0000, v132
	v_lshlrev_b32_e32 v132, 16, v133
	v_and_b32_e32 v133, 0xffff0000, v133
	v_lshlrev_b64 v[130:131], 11, v[130:131]
	v_pk_fma_f32 v[18:19], v[134:135], s[94:95], v[18:19] op_sel_hi:[1,0,1]
	v_pk_fma_f32 v[10:11], v[132:133], s[94:95], v[10:11] op_sel_hi:[1,0,1]
	v_pk_fma_f32 v[8:9], v[136:137], s[94:95], v[8:9] op_sel_hi:[1,0,1]
	v_lshl_add_u64 v[130:131], s[28:29], 0, v[130:131]
	v_lshl_add_u64 v[134:135], v[130:131], 0, v[140:141]
	s_waitcnt vmcnt(11)
	v_mov_b32_e32 v130, v200
	v_mov_b32_e32 v131, v201
	v_mov_b32_e32 v132, v202
	v_mov_b32_e32 v133, v203
	v_lshlrev_b32_e32 v136, 16, v130
	v_and_b32_e32 v137, 0xffff0000, v130
	v_lshlrev_b32_e32 v130, 16, v131
	v_and_b32_e32 v131, 0xffff0000, v131
	v_lshlrev_b32_e32 v142, 16, v132
	v_and_b32_e32 v143, 0xffff0000, v132
	v_lshlrev_b32_e32 v132, 16, v133
	v_and_b32_e32 v133, 0xffff0000, v133
	v_pk_fma_f32 v[48:49], v[130:131], s[94:95], v[48:49] op_sel_hi:[1,0,1]
	v_pk_fma_f32 v[40:41], v[132:133], s[94:95], v[40:41] op_sel_hi:[1,0,1]
	v_pk_fma_f32 v[46:47], v[136:137], s[94:95], v[46:47] op_sel_hi:[1,0,1]
	v_pk_fma_f32 v[38:39], v[142:143], s[94:95], v[38:39] op_sel_hi:[1,0,1]
	s_waitcnt vmcnt(10)
	v_mov_b32_e32 v130, v204
	v_mov_b32_e32 v131, v205
	v_mov_b32_e32 v132, v206
	v_mov_b32_e32 v133, v207
	v_lshlrev_b32_e32 v134, 16, v130
	v_and_b32_e32 v135, 0xffff0000, v130
	v_lshlrev_b32_e32 v130, 16, v131
	v_and_b32_e32 v131, 0xffff0000, v131
	v_pk_fma_f32 v[44:45], v[130:131], s[94:95], v[44:45] op_sel_hi:[1,0,1]
	v_or_b32_e32 v130, 48, v138
	v_ashrrev_i32_e32 v131, 31, v130
	v_lshlrev_b64 v[130:131], 11, v[130:131]
	v_lshlrev_b32_e32 v136, 16, v132
	v_and_b32_e32 v137, 0xffff0000, v132
	v_lshlrev_b32_e32 v132, 16, v133
	v_and_b32_e32 v133, 0xffff0000, v133
	v_lshl_add_u64 v[130:131], s[28:29], 0, v[130:131]
	v_pk_fma_f32 v[42:43], v[134:135], s[94:95], v[42:43] op_sel_hi:[1,0,1]
	v_pk_fma_f32 v[36:37], v[132:133], s[94:95], v[36:37] op_sel_hi:[1,0,1]
	v_pk_fma_f32 v[34:35], v[136:137], s[94:95], v[34:35] op_sel_hi:[1,0,1]
	v_lshl_add_u64 v[134:135], v[130:131], 0, v[140:141]
	s_waitcnt vmcnt(9)
	v_mov_b32_e32 v130, v208
	v_mov_b32_e32 v131, v209
	v_mov_b32_e32 v132, v210
	v_mov_b32_e32 v133, v211
	v_lshlrev_b32_e32 v136, 16, v130
	v_and_b32_e32 v137, 0xffff0000, v130
	v_lshlrev_b32_e32 v130, 16, v131
	v_and_b32_e32 v131, 0xffff0000, v131
	v_lshlrev_b32_e32 v142, 16, v132
	v_and_b32_e32 v143, 0xffff0000, v132
	v_lshlrev_b32_e32 v132, 16, v133
	v_and_b32_e32 v133, 0xffff0000, v133
	v_pk_fma_f32 v[64:65], v[130:131], s[94:95], v[64:65] op_sel_hi:[1,0,1]
	v_pk_fma_f32 v[56:57], v[132:133], s[94:95], v[56:57] op_sel_hi:[1,0,1]
	v_pk_fma_f32 v[62:63], v[136:137], s[94:95], v[62:63] op_sel_hi:[1,0,1]
	v_pk_fma_f32 v[54:55], v[142:143], s[94:95], v[54:55] op_sel_hi:[1,0,1]
	s_waitcnt vmcnt(8)
	v_mov_b32_e32 v130, v212
	v_mov_b32_e32 v131, v213
	v_mov_b32_e32 v132, v214
	v_mov_b32_e32 v133, v215
	v_lshlrev_b32_e32 v134, 16, v130
	v_and_b32_e32 v135, 0xffff0000, v130
	v_lshlrev_b32_e32 v130, 16, v131
	v_and_b32_e32 v131, 0xffff0000, v131
	v_pk_fma_f32 v[60:61], v[130:131], s[94:95], v[60:61] op_sel_hi:[1,0,1]
	v_add_u32_e32 v130, 0x80, v138
	v_ashrrev_i32_e32 v131, 31, v130
	v_lshlrev_b32_e32 v136, 16, v132
	v_and_b32_e32 v137, 0xffff0000, v132
	v_lshlrev_b32_e32 v132, 16, v133
	v_and_b32_e32 v133, 0xffff0000, v133
	v_lshlrev_b64 v[130:131], 11, v[130:131]
	v_pk_fma_f32 v[58:59], v[134:135], s[94:95], v[58:59] op_sel_hi:[1,0,1]
	v_pk_fma_f32 v[52:53], v[132:133], s[94:95], v[52:53] op_sel_hi:[1,0,1]
	v_pk_fma_f32 v[50:51], v[136:137], s[94:95], v[50:51] op_sel_hi:[1,0,1]
	v_lshl_add_u64 v[130:131], s[28:29], 0, v[130:131]
	v_lshl_add_u64 v[134:135], v[130:131], 0, v[140:141]
	s_waitcnt vmcnt(7)
	v_mov_b32_e32 v130, v216
	v_mov_b32_e32 v131, v217
	v_mov_b32_e32 v132, v218
	v_mov_b32_e32 v133, v219
	v_lshlrev_b32_e32 v136, 16, v130
	v_and_b32_e32 v137, 0xffff0000, v130
	v_lshlrev_b32_e32 v130, 16, v131
	v_and_b32_e32 v131, 0xffff0000, v131
	v_lshlrev_b32_e32 v142, 16, v132
	v_and_b32_e32 v143, 0xffff0000, v132
	v_lshlrev_b32_e32 v132, 16, v133
	v_and_b32_e32 v133, 0xffff0000, v133
	v_pk_fma_f32 v[80:81], v[130:131], s[94:95], v[80:81] op_sel_hi:[1,0,1]
	v_pk_fma_f32 v[72:73], v[132:133], s[94:95], v[72:73] op_sel_hi:[1,0,1]
	v_pk_fma_f32 v[78:79], v[136:137], s[94:95], v[78:79] op_sel_hi:[1,0,1]
	v_pk_fma_f32 v[70:71], v[142:143], s[94:95], v[70:71] op_sel_hi:[1,0,1]
	s_waitcnt vmcnt(6)
	v_mov_b32_e32 v130, v220
	v_mov_b32_e32 v131, v221
	v_mov_b32_e32 v132, v222
	v_mov_b32_e32 v133, v223
	v_lshlrev_b32_e32 v134, 16, v130
	v_and_b32_e32 v135, 0xffff0000, v130
	v_lshlrev_b32_e32 v130, 16, v131
	v_and_b32_e32 v131, 0xffff0000, v131
	v_pk_fma_f32 v[76:77], v[130:131], s[94:95], v[76:77] op_sel_hi:[1,0,1]
	v_add_u32_e32 v130, 0x90, v138
	v_ashrrev_i32_e32 v131, 31, v130
	v_lshlrev_b64 v[130:131], 11, v[130:131]
	v_lshlrev_b32_e32 v136, 16, v132
	v_and_b32_e32 v137, 0xffff0000, v132
	v_lshlrev_b32_e32 v132, 16, v133
	v_and_b32_e32 v133, 0xffff0000, v133
	v_lshl_add_u64 v[130:131], s[28:29], 0, v[130:131]
	v_pk_fma_f32 v[74:75], v[134:135], s[94:95], v[74:75] op_sel_hi:[1,0,1]
	v_pk_fma_f32 v[68:69], v[132:133], s[94:95], v[68:69] op_sel_hi:[1,0,1]
	v_pk_fma_f32 v[66:67], v[136:137], s[94:95], v[66:67] op_sel_hi:[1,0,1]
	v_lshl_add_u64 v[134:135], v[130:131], 0, v[140:141]
	s_waitcnt vmcnt(5)
	v_mov_b32_e32 v130, v224
	v_mov_b32_e32 v131, v225
	v_mov_b32_e32 v132, v226
	v_mov_b32_e32 v133, v227
	v_lshlrev_b32_e32 v136, 16, v130
	v_and_b32_e32 v137, 0xffff0000, v130
	v_lshlrev_b32_e32 v130, 16, v131
	v_and_b32_e32 v131, 0xffff0000, v131
	v_lshlrev_b32_e32 v142, 16, v132
	v_and_b32_e32 v143, 0xffff0000, v132
	v_lshlrev_b32_e32 v132, 16, v133
	v_and_b32_e32 v133, 0xffff0000, v133
	v_pk_fma_f32 v[112:113], v[130:131], s[94:95], v[112:113] op_sel_hi:[1,0,1]
	v_pk_fma_f32 v[100:101], v[132:133], s[94:95], v[100:101] op_sel_hi:[1,0,1]
	v_pk_fma_f32 v[110:111], v[136:137], s[94:95], v[110:111] op_sel_hi:[1,0,1]
	v_pk_fma_f32 v[98:99], v[142:143], s[94:95], v[98:99] op_sel_hi:[1,0,1]
	s_waitcnt vmcnt(4)
	v_mov_b32_e32 v130, v228
	v_mov_b32_e32 v131, v229
	v_mov_b32_e32 v132, v230
	v_mov_b32_e32 v133, v231
	v_lshlrev_b32_e32 v134, 16, v130
	v_and_b32_e32 v135, 0xffff0000, v130
	v_lshlrev_b32_e32 v130, 16, v131
	v_and_b32_e32 v131, 0xffff0000, v131
	v_pk_fma_f32 v[108:109], v[130:131], s[94:95], v[108:109] op_sel_hi:[1,0,1]
	v_add_u32_e32 v130, 0xa0, v138
	v_ashrrev_i32_e32 v131, 31, v130
	v_lshlrev_b32_e32 v136, 16, v132
	v_and_b32_e32 v137, 0xffff0000, v132
	v_lshlrev_b32_e32 v132, 16, v133
	v_and_b32_e32 v133, 0xffff0000, v133
	v_lshlrev_b64 v[130:131], 11, v[130:131]
	v_pk_fma_f32 v[106:107], v[134:135], s[94:95], v[106:107] op_sel_hi:[1,0,1]
	v_pk_fma_f32 v[96:97], v[132:133], s[94:95], v[96:97] op_sel_hi:[1,0,1]
	v_pk_fma_f32 v[94:95], v[136:137], s[94:95], v[94:95] op_sel_hi:[1,0,1]
	v_lshl_add_u64 v[130:131], s[28:29], 0, v[130:131]
	v_lshl_add_u64 v[142:143], v[130:131], 0, v[140:141]
	s_waitcnt vmcnt(3)
	v_mov_b32_e32 v130, v232
	v_mov_b32_e32 v131, v233
	v_mov_b32_e32 v132, v234
	v_mov_b32_e32 v133, v235
	v_lshlrev_b32_e32 v134, 16, v130
	v_and_b32_e32 v135, 0xffff0000, v130
	v_lshlrev_b32_e32 v130, 16, v131
	v_and_b32_e32 v131, 0xffff0000, v131
	v_lshlrev_b32_e32 v146, 16, v132
	v_and_b32_e32 v147, 0xffff0000, v132
	v_lshlrev_b32_e32 v132, 16, v133
	v_and_b32_e32 v133, 0xffff0000, v133
	v_pk_fma_f32 v[136:137], v[130:131], s[94:95], v[128:129] op_sel_hi:[1,0,1]
	v_pk_fma_f32 v[134:135], v[134:135], s[94:95], v[126:127] op_sel_hi:[1,0,1]
	v_pk_fma_f32 v[128:129], v[132:133], s[94:95], v[124:125] op_sel_hi:[1,0,1]
	v_pk_fma_f32 v[126:127], v[146:147], s[94:95], v[122:123] op_sel_hi:[1,0,1]
	s_waitcnt vmcnt(2)
	v_mov_b32_e32 v122, v148
	v_mov_b32_e32 v123, v149
	v_mov_b32_e32 v124, v150
	v_mov_b32_e32 v125, v151
	v_lshlrev_b32_e32 v130, 16, v122
	v_and_b32_e32 v131, 0xffff0000, v122
	v_lshlrev_b32_e32 v122, 16, v123
	v_and_b32_e32 v123, 0xffff0000, v123
	v_lshlrev_b32_e32 v142, 16, v124
	v_and_b32_e32 v143, 0xffff0000, v124
	v_pk_fma_f32 v[132:133], v[122:123], s[94:95], v[104:105] op_sel_hi:[1,0,1]
	v_pk_fma_f32 v[122:123], v[142:143], s[94:95], v[90:91] op_sel_hi:[1,0,1]
	v_add_u32_e32 v90, 0xb0, v138
	v_ashrrev_i32_e32 v91, 31, v90
	v_lshlrev_b64 v[90:91], 11, v[90:91]
	v_lshlrev_b32_e32 v124, 16, v125
	v_and_b32_e32 v125, 0xffff0000, v125
	v_lshl_add_u64 v[90:91], s[28:29], 0, v[90:91]
	v_pk_fma_f32 v[130:131], v[130:131], s[94:95], v[102:103] op_sel_hi:[1,0,1]
	v_pk_fma_f32 v[124:125], v[124:125], s[94:95], v[92:93] op_sel_hi:[1,0,1]
	v_lshl_add_u64 v[138:139], v[90:91], 0, v[140:141]
	s_waitcnt vmcnt(1)
	v_mov_b32_e32 v90, v152
	v_mov_b32_e32 v91, v153
	v_mov_b32_e32 v92, v154
	v_mov_b32_e32 v93, v155
	v_lshlrev_b32_e32 v102, 16, v90
	v_and_b32_e32 v103, 0xffff0000, v90
	v_lshlrev_b32_e32 v90, 16, v91
	v_and_b32_e32 v91, 0xffff0000, v91
	v_lshlrev_b32_e32 v140, 16, v92
	v_and_b32_e32 v141, 0xffff0000, v92
	v_lshlrev_b32_e32 v92, 16, v93
	v_and_b32_e32 v93, 0xffff0000, v93
	v_pk_fma_f32 v[104:105], v[90:91], s[94:95], v[120:121] op_sel_hi:[1,0,1]
	v_pk_fma_f32 v[92:93], v[92:93], s[94:95], v[116:117] op_sel_hi:[1,0,1]
	v_pk_fma_f32 v[90:91], v[140:141], s[94:95], v[114:115] op_sel_hi:[1,0,1]
	v_pk_fma_f32 v[102:103], v[102:103], s[94:95], v[118:119] op_sel_hi:[1,0,1]
	v_add_f32_e32 v139, v6, v7
	v_mov_b32_e32 v138, v1
	s_waitcnt vmcnt(0)
	v_mov_b32_e32 v114, v156
	v_mov_b32_e32 v115, v157
	v_mov_b32_e32 v116, v158
	v_mov_b32_e32 v117, v159
	v_lshlrev_b32_e32 v118, 16, v114
	v_and_b32_e32 v119, 0xffff0000, v114
	v_lshlrev_b32_e32 v114, 16, v115
	v_and_b32_e32 v115, 0xffff0000, v115
	v_pk_fma_f32 v[88:89], v[114:115], s[94:95], v[88:89] op_sel_hi:[1,0,1]
	v_and_b32_e32 v115, 64, v245
	v_lshlrev_b32_e32 v120, 16, v116
	v_and_b32_e32 v121, 0xffff0000, v116
	v_lshlrev_b32_e32 v116, 16, v117
	v_and_b32_e32 v117, 0xffff0000, v117
	v_xor_b32_e32 v114, 16, v245
	v_add_u32_e32 v115, 64, v115
	v_pk_fma_f32 v[84:85], v[116:117], s[94:95], v[84:85] op_sel_hi:[1,0,1]
	v_cmp_lt_i32_e32 vcc, v114, v115
	v_xor_b32_e32 v116, 32, v245
	v_pk_fma_f32 v[86:87], v[118:119], s[94:95], v[86:87] op_sel_hi:[1,0,1]
	v_cndmask_b32_e32 v114, v245, v114, vcc
	v_cmp_lt_i32_e32 vcc, v116, v115
	v_mov_b32_e32 v117, v32
	v_mov_b32_e32 v118, v30
	v_cndmask_b32_e32 v115, v245, v116, vcc
	v_mov_b32_e32 v116, v31
	v_mov_b32_e32 v119, v33
	v_pk_fma_f32 v[82:83], v[120:121], s[94:95], v[82:83] op_sel_hi:[1,0,1]
	v_pk_add_f32 v[116:117], v[116:117], v[118:119]
	v_mov_b32_e32 v118, v23
	v_mov_b32_e32 v119, v24
	v_mov_b32_e32 v120, v22
	v_mov_b32_e32 v121, v25
	v_pk_add_f32 v[118:119], v[118:119], v[120:121]
	v_add_f32_e32 v116, v116, v117
	v_pk_add_f32 v[118:119], v[118:119], v[118:119] op_sel_hi:[0,1]
	v_add_f32_e32 v117, 0, v116
	v_add_f32_e32 v121, v4, v5
	v_mov_b32_e32 v120, v0
	v_mov_b32_e32 v118, v2
	v_mov_b32_e32 v116, v3
	v_pk_add_f32 v[120:121], v[120:121], v[138:139]
	v_pk_add_f32 v[116:117], v[118:119], v[116:117]
	v_lshlrev_b32_e32 v114, 2, v114
	v_pk_add_f32 v[116:117], v[120:121], v[116:117]
	v_lshlrev_b32_e32 v115, 2, v115
	v_add_f32_e32 v116, v116, v117
	ds_bpermute_b32 v117, v114, v116
	v_cmp_gt_u32_e32 vcc, 16, v16
	s_waitcnt lgkmcnt(0)
	v_add_f32_e32 v116, v116, v117
	ds_bpermute_b32 v117, v115, v116
	s_waitcnt lgkmcnt(0)
	v_add_f32_e32 v116, v116, v117
	v_fmamk_f32 v118, v116, 0xbc800000, v33
	v_fmamk_f32 v120, v116, 0xbc800000, v31
	v_fmamk_f32 v117, v116, 0xbc800000, v32
	v_fmamk_f32 v119, v116, 0xbc800000, v30
	v_mul_f32_e32 v120, v120, v120
	v_mul_f32_e32 v118, v118, v118
	v_fmac_f32_e32 v120, v119, v119
	v_fmac_f32_e32 v118, v117, v117
	v_fmamk_f32 v119, v116, 0xbc800000, v25
	v_fmamk_f32 v121, v116, 0xbc800000, v23
	v_add_f32_e32 v117, v120, v118
	v_fmamk_f32 v118, v116, 0xbc800000, v24
	v_fmamk_f32 v120, v116, 0xbc800000, v22
	v_mul_f32_e32 v121, v121, v121
	v_mul_f32_e32 v119, v119, v119
	v_fmac_f32_e32 v121, v120, v120
	v_fmac_f32_e32 v119, v118, v118
	v_add_f32_e32 v118, v121, v119
	v_fmamk_f32 v119, v116, 0xbc800000, v7
	v_fmamk_f32 v121, v116, 0xbc800000, v5
	v_add_f32_e32 v117, v117, v118
	v_fmamk_f32 v118, v116, 0xbc800000, v6
	v_fmamk_f32 v120, v116, 0xbc800000, v4
	v_mul_f32_e32 v121, v121, v121
	v_mul_f32_e32 v119, v119, v119
	v_fmac_f32_e32 v121, v120, v120
	v_fmac_f32_e32 v119, v118, v118
	v_add_f32_e32 v118, v121, v119
	v_fmamk_f32 v119, v116, 0xbc800000, v3
	v_fmamk_f32 v121, v116, 0xbc800000, v1
	v_add_f32_e32 v117, v118, v117
	v_fmamk_f32 v118, v116, 0xbc800000, v2
	v_fmamk_f32 v120, v116, 0xbc800000, v0
	v_mul_f32_e32 v121, v121, v121
	v_mul_f32_e32 v119, v119, v119
	v_fmac_f32_e32 v121, v120, v120
	v_fmac_f32_e32 v119, v118, v118
	v_add_f32_e32 v118, v121, v119
	v_add_f32_e32 v117, v118, v117
	ds_bpermute_b32 v118, v114, v117
	s_waitcnt lgkmcnt(0)
	v_add_f32_e32 v117, v117, v118
	ds_bpermute_b32 v118, v115, v117
	s_and_saveexec_b64 s[4:5], vcc
	v_readlane_b32 s28, v255, 8
	s_mov_b32 s80, s28
	s_movk_i32 s90, 0x1dbf
	s_movk_i32 s91, 0x210
	s_movk_i32 s88, 0x1600
	s_mov_b32 s89, 0x16000
	s_mov_b64 s[62:63], 0x2000
	v_readlane_b32 s60, v255, 13
	v_readlane_b32 s29, v255, 9
	s_cbranch_execz .LBB0_2545
	s_lshl_b32 s7, s48, 11
	s_add_i32 s7, s6, s7
	v_mul_f32_e32 v116, 0x3c800000, v116
	v_lshl_add_u32 v119, v145, 5, s7
	s_waitcnt lgkmcnt(0)
	v_add_f32_e32 v117, v117, v118
	ds_write_b64 v119, v[116:117]
